# mixers: pool loop start tile rotated by 64 blocks so the 8-tile tails of the conv loop and the pool loop land on different blocks
# speedup vs baseline: 1.0040x; 1.0040x over previous
; #define LAS __attribute__((address_space(3)))
; DI void phase_mixers(const Params& p, int l, LAS char* lds) {
;     ...
;     for (int tile = vblock(); tile < 8 * 129; tile += gridDim.x) {
;         const int b = tile / 129, t0 = (tile - b * 129) * 32;
;         const bf16_t* zb = zc + (size_t)b * LSEQ * 2304;
;         bf16_t* ub = u + (size_t)b * LSEQ * 1280;
;         {
;             const int win = 2 << w;
;             LAS bf16_t* img = (LAS bf16_t*)(lds + 32768);
;             u32x4 pgr[4];
;             {
;                 u32x4 vv[6];
; #pragma unroll
;                 for (int it = 0; it < 6; ++it) {
;                     const int q = c + 256 * it, r = q >> 5, c8 = (q & 31) * 8, t = t0 - 15 + r;
;                     vv[it] = (u32x4){0u, 0u, 0u, 0u};
;                     if (q < 47 * 32 && t >= 0 && t < LSEQ) vv[it] = *(const u32x4*)(zb + (size_t)t * 2304 + c8);
;                 }
; #pragma unroll
;                 for (int it = 0; it < 4; ++it) {
;                     const int q = c + 256 * it, r = q >> 5, c8 = (q & 31) * 8, t = t0 + r, tc = (t < LSEQ) ? t : LSEQ - 1;
;                     pgr[it] = *(const u32x4*)(zb + (size_t)tc * 2304 + 256 + c8);
;                 }
; #pragma unroll
;                 for (int it = 0; it < 6; ++it) {
;                     const int q = c + 256 * it, r = q >> 5, c8 = (q & 31) * 8;
;                     if (q < 47 * 32) *(LAS u32x4*)(img + r * 256 + c8) = vv[it];
;                 }
;             }
;             __syncthreads();
;             {
;                 float v[47];
; #pragma unroll
;                 for (int i = 0; i < 47; ++i) v[i] = bf2f(img[i * 256 + c]);
; #pragma unroll
;                 for (int tt = 0; tt < 32; ++tt) {
;                     float s = 0.f;
; #pragma unroll
;                     for (int j = 0; j < 16; ++j) s += (j < win) ? v[tt + 15 - j] : 0.f;
;                     const int t = t0 + tt;
;                     const float cnt = (float)((t + 1 < win) ? t + 1 : win);
;                     ybuf[tt * 256 + c] = s * __builtin_amdgcn_rcpf(cnt) - v[tt + 15];
;                 }
;             }
;             __syncthreads();
; #pragma unroll
;             for (int it = 0; it < 4; ++it) { const int q = c + 256 * it, r = q >> 5, c8 = (q & 31) * 8; *(LAS u32x4*)(img + r * 256 + c8) = pgr[it]; }
;             __syncthreads();
;             asm volatile("" ::: "memory");
;             float W[64];
.LBB0_326:
	s_add_i32 s23, s23, s3
	s_add_i32 s23, s23, 0xffffffc0
	s_add_i32 s4, s3, -1
	s_and_b32 s23, s23, s4
	v_readlane_b32 s0, v228, 30
	v_readlane_b32 s4, v229, 45
	v_readlane_b32 s14, v229, 55
	s_waitcnt vmcnt(0)
	v_lshl_add_u32 v2, s0, 2, v101
	v_readlane_b32 s0, v231, 2
	v_readlane_b32 s1, v231, 3
	v_ashrrev_i32_e32 v3, 31, v2
	v_lshlrev_b64 v[2:3], 14, v[2:3]
	v_lshl_add_u64 v[42:43], v[102:103], 1, s[0:1]
	s_movk_i32 s0, 0x5e0
	v_cmp_gt_i32_e32 vcc, s0, v102
	s_movk_i32 s0, 0x4e0
	v_cmp_gt_i32_e64 s[38:39], s0, v102
	s_movk_i32 s0, 0x3e0
	v_cmp_gt_i32_e64 s[40:41], s0, v102
	s_movk_i32 s0, 0x2e0
	v_cmp_gt_i32_e64 s[42:43], s0, v102
	s_movk_i32 s0, 0x1e0
	v_cmp_gt_i32_e64 s[44:45], s0, v102
	s_movk_i32 s0, 0xe0
	v_readlane_b32 s15, v229, 56
	v_lshlrev_b32_e64 v184, v101, 2
	v_lshlrev_b32_e32 v4, 1, v98
	v_cmp_gt_i32_e64 s[46:47], s0, v102
	s_movk_i32 s0, 0xfe00
	v_lshl_add_u64 v[2:3], s[14:15], 0, v[2:3]
	v_mov_b32_e32 v101, v149
	v_and_or_b32 v186, v138, s0, v4
	v_and_or_b32 v187, v140, s0, v4
	v_and_or_b32 v188, v141, s0, v4
	v_and_or_b32 v189, v142, s0, v4
	v_and_or_b32 v190, v143, s0, v4
	v_and_or_b32 v191, v139, s0, v4
	v_lshl_add_u64 v[44:45], v[2:3], 0, v[100:101]
	s_mov_b64 s[0:1], 0x1000
	v_lshl_add_u64 v[46:47], v[44:45], 0, s[0:1]
	s_mov_b64 s[0:1], 0x1100
	v_lshl_add_u64 v[48:49], v[44:45], 0, s[0:1]
	s_mov_b64 s[0:1], 0x1200
	v_lshl_add_u64 v[50:51], v[44:45], 0, s[0:1]
	s_mov_b64 s[0:1], 0x1300
	v_lshl_add_u64 v[52:53], v[44:45], 0, s[0:1]
	s_mov_b64 s[0:1], 0x1400
	v_lshl_add_u64 v[54:55], v[44:45], 0, s[0:1]
	s_mov_b64 s[0:1], 0x1500
	v_lshl_add_u64 v[56:57], v[44:45], 0, s[0:1]
	s_mov_b64 s[0:1], 0x1600
	v_lshl_add_u64 v[58:59], v[44:45], 0, s[0:1]
	s_mov_b64 s[0:1], 0x1700
	v_lshl_add_u64 v[60:61], v[44:45], 0, s[0:1]
	s_mov_b64 s[0:1], 0x1800
	v_lshl_add_u64 v[62:63], v[44:45], 0, s[0:1]
	s_mov_b64 s[0:1], 0x1900
	v_lshl_add_u64 v[64:65], v[44:45], 0, s[0:1]
	s_mov_b64 s[0:1], 0x1a00
	v_lshl_add_u64 v[68:69], v[44:45], 0, s[0:1]
	s_mov_b64 s[0:1], 0x1b00
	v_lshl_add_u64 v[70:71], v[44:45], 0, s[0:1]
	s_mov_b64 s[0:1], 0x1c00
	v_lshl_add_u64 v[72:73], v[44:45], 0, s[0:1]
	s_mov_b64 s[0:1], 0x1d00
	v_lshl_add_u64 v[74:75], v[44:45], 0, s[0:1]
	s_mov_b64 s[0:1], 0x1e00
	v_lshl_add_u64 v[76:77], v[44:45], 0, s[0:1]
	s_mov_b64 s[0:1], 0x1f00
	v_lshl_add_u64 v[78:79], v[44:45], 0, s[0:1]
	s_mov_b64 s[0:1], 0x2000
	v_lshl_add_u64 v[80:81], v[44:45], 0, s[0:1]
	s_mov_b64 s[0:1], 0x2100
	v_lshl_add_u64 v[82:83], v[44:45], 0, s[0:1]
	s_mov_b64 s[0:1], 0x2200
	v_lshl_add_u64 v[84:85], v[44:45], 0, s[0:1]
	s_mov_b64 s[0:1], 0x2300
	v_lshl_add_u64 v[86:87], v[44:45], 0, s[0:1]
	s_mov_b64 s[0:1], 0x2400
	v_lshl_add_u64 v[88:89], v[44:45], 0, s[0:1]
	s_mov_b64 s[0:1], 0x2500
	v_lshl_add_u64 v[90:91], v[44:45], 0, s[0:1]
	s_mov_b64 s[0:1], 0x2600
	v_lshl_add_u64 v[92:93], v[44:45], 0, s[0:1]
	s_mov_b64 s[0:1], 0x2700
	v_lshl_add_u64 v[94:95], v[44:45], 0, s[0:1]
	s_mov_b64 s[0:1], 0x2800
	v_lshl_add_u64 v[96:97], v[44:45], 0, s[0:1]
	s_mov_b64 s[0:1], 0x2900
	v_lshl_add_u64 v[100:101], v[44:45], 0, s[0:1]
	s_mov_b64 s[0:1], 0x2a00
	v_and_b32_e32 v5, 0x3fffffc0, v102
	v_lshl_add_u64 v[102:103], v[44:45], 0, s[0:1]
	s_mov_b64 s[0:1], 0x2b00
	v_lshl_add_u64 v[104:105], v[44:45], 0, s[0:1]
	s_mov_b64 s[0:1], 0x2c00
	v_lshl_add_u64 v[106:107], v[44:45], 0, s[0:1]
	s_mov_b64 s[0:1], 0x2d00
	v_lshl_add_u64 v[108:109], v[44:45], 0, s[0:1]
	s_mov_b64 s[0:1], 0x2e00
	v_lshl_add_u64 v[110:111], v[44:45], 0, s[0:1]
	s_mov_b64 s[0:1], 0x2f00
	v_lshl_add_u64 v[112:113], v[44:45], 0, s[0:1]
	s_mov_b64 s[0:1], 0x3000
	v_lshl_add_u64 v[114:115], v[44:45], 0, s[0:1]
	s_mov_b64 s[0:1], 0x3100
	v_lshl_add_u64 v[116:117], v[44:45], 0, s[0:1]
	s_mov_b64 s[0:1], 0x3200
	v_lshl_add_u64 v[118:119], v[44:45], 0, s[0:1]
	s_mov_b64 s[0:1], 0x3300
	v_lshl_add_u64 v[120:121], v[44:45], 0, s[0:1]
	s_mov_b64 s[0:1], 0x3400
	v_lshl_add_u64 v[122:123], v[44:45], 0, s[0:1]
	s_mov_b64 s[0:1], 0x3500
	v_lshl_add_u64 v[124:125], v[44:45], 0, s[0:1]
	s_mov_b64 s[0:1], 0x3600
	v_lshl_add_u64 v[126:127], v[44:45], 0, s[0:1]
	s_mov_b64 s[0:1], 0x3700
	v_lshl_add_u64 v[128:129], v[44:45], 0, s[0:1]
	s_mov_b64 s[0:1], 0x3800
	v_lshl_add_u64 v[130:131], v[44:45], 0, s[0:1]
	s_mov_b64 s[0:1], 0x3900
	v_lshl_add_u64 v[132:133], v[44:45], 0, s[0:1]
	s_mov_b64 s[0:1], 0x3a00
	v_lshl_add_u64 v[134:135], v[44:45], 0, s[0:1]
	s_mov_b64 s[0:1], 0x3b00
	v_lshl_add_u64 v[136:137], v[44:45], 0, s[0:1]
	s_mov_b64 s[0:1], 0x3c00
	v_lshl_add_u64 v[138:139], v[44:45], 0, s[0:1]
	s_mov_b64 s[0:1], 0x3d00
	v_readlane_b32 s12, v229, 53
	v_readlane_b32 s13, v229, 54
	v_readlane_b32 s16, v229, 57
	v_readlane_b32 s17, v229, 58
	v_readlane_b32 s18, v229, 59
	v_readlane_b32 s19, v229, 60
	v_lshl_add_u64 v[140:141], v[44:45], 0, s[0:1]
	s_mov_b64 s[0:1], 0x3e00
	v_readlane_b32 s8, v229, 49
	v_readlane_b32 s10, v229, 51
	v_readlane_b32 s12, v228, 19
	v_readlane_b32 s18, v228, 17
	v_readlane_b32 s14, v229, 61
	v_lshl_add_u64 v[142:143], v[44:45], 0, s[0:1]
	s_mov_b64 s[0:1], 0x3f00
	v_lshl_add_u64 v[66:67], v[66:67], 2, s[16:17]
	v_readlane_b32 s16, v229, 63
	v_lshlrev_b32_e32 v185, 2, v5
	v_cmp_lt_i32_e64 s[48:49], 0, v184
	v_cmp_lt_i32_e64 s[50:51], 1, v184
	v_cmp_lt_i32_e64 s[52:53], 2, v184
	v_cmp_lt_i32_e64 s[54:55], 3, v184
	v_cmp_lt_i32_e64 s[56:57], 4, v184
	v_cmp_lt_i32_e64 s[58:59], 5, v184
	v_cmp_lt_i32_e64 s[60:61], 6, v184
	v_cmp_lt_i32_e64 s[62:63], 7, v184
	v_cmp_lt_i32_e64 s[64:65], 8, v184
	v_cmp_lt_i32_e64 s[66:67], 9, v184
	v_cmp_lt_i32_e64 s[68:69], 10, v184
	v_cmp_lt_i32_e64 s[70:71], 11, v184
	v_cmp_lt_i32_e64 s[72:73], 12, v184
	v_cmp_lt_i32_e64 s[74:75], 13, v184
	v_cmp_lt_i32_e64 s[76:77], 14, v184
	v_cmp_lt_i32_e64 s[78:79], 15, v184
	s_movk_i32 s8, 0x900
	s_mov_b32 s10, 0x800000
	v_readlane_b32 s13, v228, 20
	v_readlane_b32 s19, v228, 18
	v_readlane_b32 s15, v229, 62
	v_lshl_add_u64 v[144:145], v[44:45], 0, s[0:1]
	v_readlane_b32 s17, v228, 0
	v_add_u32_e32 v192, 0x8000, v1
	s_lshl_b32 s1, s23, 5
	s_lshl_b32 s34, s3, 5
	v_readlane_b32 s5, v229, 46
	v_readlane_b32 s6, v229, 47
	v_readlane_b32 s7, v229, 48
	v_readlane_b32 s9, v229, 50
	v_readlane_b32 s11, v229, 52
	s_branch .LBB0_328
